# NSA compressed-branch pass 1 loop: counted vmcnt so the next tile's loads stay in flight
# speedup vs baseline: 1.0015x; 1.0015x over previous
.LBB0_223:
	s_cmp_lg_u64 s[44:45], 0
	s_cbranch_scc0 .Lc1_ev_w0
	s_waitcnt vmcnt(2)
	s_branch .Lc1_ev_st

.Lc1_ev_st:
	ds_write_b128 v145, v[90:93] offset:9216
	ds_write_b128 v124, v[94:97] offset:30720

.LBB0_233:
	s_andn2_b64 vcc, exec, s[44:45]
	s_cbranch_vccnz .LBB0_235
	s_cmp_lg_u64 s[48:49], 0
	s_cbranch_scc1 .Lc1_od_w0
	s_waitcnt vmcnt(2)
	s_branch .Lc1_od_st

.Lc1_od_st:
	ds_write_b128 v123, v[102:105]
	ds_write_b128 v124, v[98:101] offset:18432
